# combined: packed-f32 sigmoid/SwiGLU epilogues (input projection gates, gate/up GEMM) + relaxed first two waits per tile in the gate/up GEMM
# baseline (speedup 1.0000x reference)
.Lgate_epi:
	v_and_b32_e32 v136, 63, v193
	v_lshrrev_b32_e32 v156, 6, v193
	v_and_b32_e32 v146, 15, v136
	v_lshrrev_b32_e32 v147, 4, v136
	v_lshlrev_b32_e32 v147, 4, v147
	v_lshl_add_u32 v148, v146, 12, v147
	v_readfirstlane_b32 s98, v156
	s_nop 3
	s_and_b32 s99, s98, 3
	s_lshr_b32 s98, s98, 2
	s_lshl_b32 s99, s99, 6
	s_lshl_b32 s98, s98, 18
	s_add_i32 s98, s98, s99
	s_lshl_b32 s99, s4, 12
	s_add_i32 s98, s98, s99
	s_sub_i32 s99, s8, 0x800
	s_lshl_b32 s99, s99, 1
	s_add_i32 s98, s98, s99
	v_add_u32_e32 v148, s98, v148
	v_mov_b32_e32 v149, 0
	v_lshl_add_u64 v[148:149], s[24:25], 0, v[148:149]
	s_mov_b32 s99, 0
	s_mov_b32 s100, 0xbfb8aa3b
	s_mov_b32 s101, 0xbfb8aa3b
	v_pk_mul_f32 v[124:125], v[124:125], s[100:101]
	v_pk_mul_f32 v[126:127], v[126:127], s[100:101]
	v_pk_mul_f32 v[120:121], v[120:121], s[100:101]
	v_pk_mul_f32 v[122:123], v[122:123], s[100:101]
	v_exp_f32_e32 v124, v124
	v_exp_f32_e32 v125, v125
	v_exp_f32_e32 v126, v126
	v_exp_f32_e32 v127, v127
	v_exp_f32_e32 v120, v120
	v_exp_f32_e32 v121, v121
	v_exp_f32_e32 v122, v122
	v_exp_f32_e32 v123, v123
	v_pk_add_f32 v[124:125], v[124:125], 1.0 op_sel_hi:[1,0]
	v_pk_add_f32 v[126:127], v[126:127], 1.0 op_sel_hi:[1,0]
	v_pk_add_f32 v[120:121], v[120:121], 1.0 op_sel_hi:[1,0]
	v_pk_add_f32 v[122:123], v[122:123], 1.0 op_sel_hi:[1,0]
	v_rcp_f32_e32 v124, v124
	v_rcp_f32_e32 v125, v125
	v_rcp_f32_e32 v126, v126
	v_rcp_f32_e32 v127, v127
	v_rcp_f32_e32 v120, v120
	v_rcp_f32_e32 v121, v121
	v_rcp_f32_e32 v122, v122
	v_rcp_f32_e32 v123, v123
	v_cvt_pk_bf16_f32 v152, v124, v125
	v_cvt_pk_bf16_f32 v153, v126, v127
	v_cvt_pk_bf16_f32 v154, v120, v121
	s_nop 0
	v_cvt_pk_bf16_f32 v155, v122, v123
	global_store_dwordx4 v[148:149], v[152:155], off nt
	v_pk_mul_f32 v[116:117], v[116:117], s[100:101]
	v_pk_mul_f32 v[118:119], v[118:119], s[100:101]
	v_pk_mul_f32 v[112:113], v[112:113], s[100:101]
	v_pk_mul_f32 v[114:115], v[114:115], s[100:101]
	v_exp_f32_e32 v116, v116
	v_exp_f32_e32 v117, v117
	v_exp_f32_e32 v118, v118
	v_exp_f32_e32 v119, v119
	v_exp_f32_e32 v112, v112
	v_exp_f32_e32 v113, v113
	v_exp_f32_e32 v114, v114
	v_exp_f32_e32 v115, v115
	v_pk_add_f32 v[116:117], v[116:117], 1.0 op_sel_hi:[1,0]
	v_pk_add_f32 v[118:119], v[118:119], 1.0 op_sel_hi:[1,0]
	v_pk_add_f32 v[112:113], v[112:113], 1.0 op_sel_hi:[1,0]
	v_pk_add_f32 v[114:115], v[114:115], 1.0 op_sel_hi:[1,0]
	v_rcp_f32_e32 v116, v116
	v_rcp_f32_e32 v117, v117
	v_rcp_f32_e32 v118, v118
	v_rcp_f32_e32 v119, v119
	v_rcp_f32_e32 v112, v112
	v_rcp_f32_e32 v113, v113
	v_rcp_f32_e32 v114, v114
	v_rcp_f32_e32 v115, v115
	v_cvt_pk_bf16_f32 v164, v116, v117
	v_cvt_pk_bf16_f32 v165, v118, v119
	v_cvt_pk_bf16_f32 v166, v112, v113
	s_nop 0
	v_cvt_pk_bf16_f32 v167, v114, v115
	global_store_dwordx4 v[148:149], v[164:167], off offset:256 nt
	s_mov_b32 s98, 0x10000
	v_lshl_add_u64 v[150:151], v[148:149], 0, s[98:99]
	v_pk_mul_f32 v[108:109], v[108:109], s[100:101]
	v_pk_mul_f32 v[110:111], v[110:111], s[100:101]
	v_pk_mul_f32 v[104:105], v[104:105], s[100:101]
	v_pk_mul_f32 v[106:107], v[106:107], s[100:101]
	v_exp_f32_e32 v108, v108
	v_exp_f32_e32 v109, v109
	v_exp_f32_e32 v110, v110
	v_exp_f32_e32 v111, v111
	v_exp_f32_e32 v104, v104
	v_exp_f32_e32 v105, v105
	v_exp_f32_e32 v106, v106
	v_exp_f32_e32 v107, v107
	v_pk_add_f32 v[108:109], v[108:109], 1.0 op_sel_hi:[1,0]
	v_pk_add_f32 v[110:111], v[110:111], 1.0 op_sel_hi:[1,0]
	v_pk_add_f32 v[104:105], v[104:105], 1.0 op_sel_hi:[1,0]
	v_pk_add_f32 v[106:107], v[106:107], 1.0 op_sel_hi:[1,0]
	v_rcp_f32_e32 v108, v108
	v_rcp_f32_e32 v109, v109
	v_rcp_f32_e32 v110, v110
	v_rcp_f32_e32 v111, v111
	v_rcp_f32_e32 v104, v104
	v_rcp_f32_e32 v105, v105
	v_rcp_f32_e32 v106, v106
	v_rcp_f32_e32 v107, v107
	v_cvt_pk_bf16_f32 v152, v108, v109
	v_cvt_pk_bf16_f32 v153, v110, v111
	v_cvt_pk_bf16_f32 v154, v104, v105
	s_nop 0
	v_cvt_pk_bf16_f32 v155, v106, v107
	global_store_dwordx4 v[150:151], v[152:155], off nt
	v_pk_mul_f32 v[100:101], v[100:101], s[100:101]
	v_pk_mul_f32 v[102:103], v[102:103], s[100:101]
	v_pk_mul_f32 v[96:97], v[96:97], s[100:101]
	v_pk_mul_f32 v[98:99], v[98:99], s[100:101]
	v_exp_f32_e32 v100, v100
	v_exp_f32_e32 v101, v101
	v_exp_f32_e32 v102, v102
	v_exp_f32_e32 v103, v103
	v_exp_f32_e32 v96, v96
	v_exp_f32_e32 v97, v97
	v_exp_f32_e32 v98, v98
	v_exp_f32_e32 v99, v99
	v_pk_add_f32 v[100:101], v[100:101], 1.0 op_sel_hi:[1,0]
	v_pk_add_f32 v[102:103], v[102:103], 1.0 op_sel_hi:[1,0]
	v_pk_add_f32 v[96:97], v[96:97], 1.0 op_sel_hi:[1,0]
	v_pk_add_f32 v[98:99], v[98:99], 1.0 op_sel_hi:[1,0]
	v_rcp_f32_e32 v100, v100
	v_rcp_f32_e32 v101, v101
	v_rcp_f32_e32 v102, v102
	v_rcp_f32_e32 v103, v103
	v_rcp_f32_e32 v96, v96
	v_rcp_f32_e32 v97, v97
	v_rcp_f32_e32 v98, v98
	v_rcp_f32_e32 v99, v99
	v_cvt_pk_bf16_f32 v164, v100, v101
	v_cvt_pk_bf16_f32 v165, v102, v103
	v_cvt_pk_bf16_f32 v166, v96, v97
	s_nop 0
	v_cvt_pk_bf16_f32 v167, v98, v99
	global_store_dwordx4 v[150:151], v[164:167], off offset:256 nt
	s_mov_b32 s98, 0x20000
	v_lshl_add_u64 v[150:151], v[148:149], 0, s[98:99]
	v_pk_mul_f32 v[92:93], v[92:93], s[100:101]
	v_pk_mul_f32 v[94:95], v[94:95], s[100:101]
	v_pk_mul_f32 v[88:89], v[88:89], s[100:101]
	v_pk_mul_f32 v[90:91], v[90:91], s[100:101]
	v_exp_f32_e32 v92, v92
	v_exp_f32_e32 v93, v93
	v_exp_f32_e32 v94, v94
	v_exp_f32_e32 v95, v95
	v_exp_f32_e32 v88, v88
	v_exp_f32_e32 v89, v89
	v_exp_f32_e32 v90, v90
	v_exp_f32_e32 v91, v91
	v_pk_add_f32 v[92:93], v[92:93], 1.0 op_sel_hi:[1,0]
	v_pk_add_f32 v[94:95], v[94:95], 1.0 op_sel_hi:[1,0]
	v_pk_add_f32 v[88:89], v[88:89], 1.0 op_sel_hi:[1,0]
	v_pk_add_f32 v[90:91], v[90:91], 1.0 op_sel_hi:[1,0]
	v_rcp_f32_e32 v92, v92
	v_rcp_f32_e32 v93, v93
	v_rcp_f32_e32 v94, v94
	v_rcp_f32_e32 v95, v95
	v_rcp_f32_e32 v88, v88
	v_rcp_f32_e32 v89, v89
	v_rcp_f32_e32 v90, v90
	v_rcp_f32_e32 v91, v91
	v_cvt_pk_bf16_f32 v152, v92, v93
	v_cvt_pk_bf16_f32 v153, v94, v95
	v_cvt_pk_bf16_f32 v154, v88, v89
	s_nop 0
	v_cvt_pk_bf16_f32 v155, v90, v91
	global_store_dwordx4 v[150:151], v[152:155], off nt
	v_pk_mul_f32 v[84:85], v[84:85], s[100:101]
	v_pk_mul_f32 v[86:87], v[86:87], s[100:101]
	v_pk_mul_f32 v[80:81], v[80:81], s[100:101]
	v_pk_mul_f32 v[82:83], v[82:83], s[100:101]
	v_exp_f32_e32 v84, v84
	v_exp_f32_e32 v85, v85
	v_exp_f32_e32 v86, v86
	v_exp_f32_e32 v87, v87
	v_exp_f32_e32 v80, v80
	v_exp_f32_e32 v81, v81
	v_exp_f32_e32 v82, v82
	v_exp_f32_e32 v83, v83
	v_pk_add_f32 v[84:85], v[84:85], 1.0 op_sel_hi:[1,0]
	v_pk_add_f32 v[86:87], v[86:87], 1.0 op_sel_hi:[1,0]
	v_pk_add_f32 v[80:81], v[80:81], 1.0 op_sel_hi:[1,0]
	v_pk_add_f32 v[82:83], v[82:83], 1.0 op_sel_hi:[1,0]
	v_rcp_f32_e32 v84, v84
	v_rcp_f32_e32 v85, v85
	v_rcp_f32_e32 v86, v86
	v_rcp_f32_e32 v87, v87
	v_rcp_f32_e32 v80, v80
	v_rcp_f32_e32 v81, v81
	v_rcp_f32_e32 v82, v82
	v_rcp_f32_e32 v83, v83
	v_cvt_pk_bf16_f32 v164, v84, v85
	v_cvt_pk_bf16_f32 v165, v86, v87
	v_cvt_pk_bf16_f32 v166, v80, v81
	s_nop 0
	v_cvt_pk_bf16_f32 v167, v82, v83
	global_store_dwordx4 v[150:151], v[164:167], off offset:256 nt
	s_mov_b32 s98, 0x30000
	v_lshl_add_u64 v[150:151], v[148:149], 0, s[98:99]
	v_pk_mul_f32 v[76:77], v[76:77], s[100:101]
	v_pk_mul_f32 v[78:79], v[78:79], s[100:101]
	v_pk_mul_f32 v[72:73], v[72:73], s[100:101]
	v_pk_mul_f32 v[74:75], v[74:75], s[100:101]
	v_exp_f32_e32 v76, v76
	v_exp_f32_e32 v77, v77
	v_exp_f32_e32 v78, v78
	v_exp_f32_e32 v79, v79
	v_exp_f32_e32 v72, v72
	v_exp_f32_e32 v73, v73
	v_exp_f32_e32 v74, v74
	v_exp_f32_e32 v75, v75
	v_pk_add_f32 v[76:77], v[76:77], 1.0 op_sel_hi:[1,0]
	v_pk_add_f32 v[78:79], v[78:79], 1.0 op_sel_hi:[1,0]
	v_pk_add_f32 v[72:73], v[72:73], 1.0 op_sel_hi:[1,0]
	v_pk_add_f32 v[74:75], v[74:75], 1.0 op_sel_hi:[1,0]
	v_rcp_f32_e32 v76, v76
	v_rcp_f32_e32 v77, v77
	v_rcp_f32_e32 v78, v78
	v_rcp_f32_e32 v79, v79
	v_rcp_f32_e32 v72, v72
	v_rcp_f32_e32 v73, v73
	v_rcp_f32_e32 v74, v74
	v_rcp_f32_e32 v75, v75
	v_cvt_pk_bf16_f32 v152, v76, v77
	v_cvt_pk_bf16_f32 v153, v78, v79
	v_cvt_pk_bf16_f32 v154, v72, v73
	s_nop 0
	v_cvt_pk_bf16_f32 v155, v74, v75
	global_store_dwordx4 v[150:151], v[152:155], off nt
	v_pk_mul_f32 v[68:69], v[68:69], s[100:101]
	v_pk_mul_f32 v[70:71], v[70:71], s[100:101]
	v_pk_mul_f32 v[64:65], v[64:65], s[100:101]
	v_pk_mul_f32 v[66:67], v[66:67], s[100:101]
	v_exp_f32_e32 v68, v68
	v_exp_f32_e32 v69, v69
	v_exp_f32_e32 v70, v70
	v_exp_f32_e32 v71, v71
	v_exp_f32_e32 v64, v64
	v_exp_f32_e32 v65, v65
	v_exp_f32_e32 v66, v66
	v_exp_f32_e32 v67, v67
	v_pk_add_f32 v[68:69], v[68:69], 1.0 op_sel_hi:[1,0]
	v_pk_add_f32 v[70:71], v[70:71], 1.0 op_sel_hi:[1,0]
	v_pk_add_f32 v[64:65], v[64:65], 1.0 op_sel_hi:[1,0]
	v_pk_add_f32 v[66:67], v[66:67], 1.0 op_sel_hi:[1,0]
	v_rcp_f32_e32 v68, v68
	v_rcp_f32_e32 v69, v69
	v_rcp_f32_e32 v70, v70
	v_rcp_f32_e32 v71, v71
	v_rcp_f32_e32 v64, v64
	v_rcp_f32_e32 v65, v65
	v_rcp_f32_e32 v66, v66
	v_rcp_f32_e32 v67, v67
	v_cvt_pk_bf16_f32 v164, v68, v69
	v_cvt_pk_bf16_f32 v165, v70, v71
	v_cvt_pk_bf16_f32 v166, v64, v65
	s_nop 0
	v_cvt_pk_bf16_f32 v167, v66, v67
	global_store_dwordx4 v[150:151], v[164:167], off offset:256 nt
	s_mov_b32 s98, 0x80000
	v_lshl_add_u64 v[150:151], v[148:149], 0, s[98:99]
	v_pk_mul_f32 v[60:61], v[60:61], s[100:101]
	v_pk_mul_f32 v[62:63], v[62:63], s[100:101]
	v_pk_mul_f32 v[56:57], v[56:57], s[100:101]
	v_pk_mul_f32 v[58:59], v[58:59], s[100:101]
	v_exp_f32_e32 v60, v60
	v_exp_f32_e32 v61, v61
	v_exp_f32_e32 v62, v62
	v_exp_f32_e32 v63, v63
	v_exp_f32_e32 v56, v56
	v_exp_f32_e32 v57, v57
	v_exp_f32_e32 v58, v58
	v_exp_f32_e32 v59, v59
	v_pk_add_f32 v[60:61], v[60:61], 1.0 op_sel_hi:[1,0]
	v_pk_add_f32 v[62:63], v[62:63], 1.0 op_sel_hi:[1,0]
	v_pk_add_f32 v[56:57], v[56:57], 1.0 op_sel_hi:[1,0]
	v_pk_add_f32 v[58:59], v[58:59], 1.0 op_sel_hi:[1,0]
	v_rcp_f32_e32 v60, v60
	v_rcp_f32_e32 v61, v61
	v_rcp_f32_e32 v62, v62
	v_rcp_f32_e32 v63, v63
	v_rcp_f32_e32 v56, v56
	v_rcp_f32_e32 v57, v57
	v_rcp_f32_e32 v58, v58
	v_rcp_f32_e32 v59, v59
	v_cvt_pk_bf16_f32 v152, v60, v61
	v_cvt_pk_bf16_f32 v153, v62, v63
	v_cvt_pk_bf16_f32 v154, v56, v57
	s_nop 0
	v_cvt_pk_bf16_f32 v155, v58, v59
	global_store_dwordx4 v[150:151], v[152:155], off nt
	v_pk_mul_f32 v[52:53], v[52:53], s[100:101]
	v_pk_mul_f32 v[54:55], v[54:55], s[100:101]
	v_pk_mul_f32 v[48:49], v[48:49], s[100:101]
	v_pk_mul_f32 v[50:51], v[50:51], s[100:101]
	v_exp_f32_e32 v52, v52
	v_exp_f32_e32 v53, v53
	v_exp_f32_e32 v54, v54
	v_exp_f32_e32 v55, v55
	v_exp_f32_e32 v48, v48
	v_exp_f32_e32 v49, v49
	v_exp_f32_e32 v50, v50
	v_exp_f32_e32 v51, v51
	v_pk_add_f32 v[52:53], v[52:53], 1.0 op_sel_hi:[1,0]
	v_pk_add_f32 v[54:55], v[54:55], 1.0 op_sel_hi:[1,0]
	v_pk_add_f32 v[48:49], v[48:49], 1.0 op_sel_hi:[1,0]
	v_pk_add_f32 v[50:51], v[50:51], 1.0 op_sel_hi:[1,0]
	v_rcp_f32_e32 v52, v52
	v_rcp_f32_e32 v53, v53
	v_rcp_f32_e32 v54, v54
	v_rcp_f32_e32 v55, v55
	v_rcp_f32_e32 v48, v48
	v_rcp_f32_e32 v49, v49
	v_rcp_f32_e32 v50, v50
	v_rcp_f32_e32 v51, v51
	v_cvt_pk_bf16_f32 v164, v52, v53
	v_cvt_pk_bf16_f32 v165, v54, v55
	v_cvt_pk_bf16_f32 v166, v48, v49
	s_nop 0
	v_cvt_pk_bf16_f32 v167, v50, v51
	global_store_dwordx4 v[150:151], v[164:167], off offset:256 nt
	s_mov_b32 s98, 0x90000
	v_lshl_add_u64 v[150:151], v[148:149], 0, s[98:99]
	v_pk_mul_f32 v[44:45], v[44:45], s[100:101]
	v_pk_mul_f32 v[46:47], v[46:47], s[100:101]
	v_pk_mul_f32 v[40:41], v[40:41], s[100:101]
	v_pk_mul_f32 v[42:43], v[42:43], s[100:101]
	v_exp_f32_e32 v44, v44
	v_exp_f32_e32 v45, v45
	v_exp_f32_e32 v46, v46
	v_exp_f32_e32 v47, v47
	v_exp_f32_e32 v40, v40
	v_exp_f32_e32 v41, v41
	v_exp_f32_e32 v42, v42
	v_exp_f32_e32 v43, v43
	v_pk_add_f32 v[44:45], v[44:45], 1.0 op_sel_hi:[1,0]
	v_pk_add_f32 v[46:47], v[46:47], 1.0 op_sel_hi:[1,0]
	v_pk_add_f32 v[40:41], v[40:41], 1.0 op_sel_hi:[1,0]
	v_pk_add_f32 v[42:43], v[42:43], 1.0 op_sel_hi:[1,0]
	v_rcp_f32_e32 v44, v44
	v_rcp_f32_e32 v45, v45
	v_rcp_f32_e32 v46, v46
	v_rcp_f32_e32 v47, v47
	v_rcp_f32_e32 v40, v40
	v_rcp_f32_e32 v41, v41
	v_rcp_f32_e32 v42, v42
	v_rcp_f32_e32 v43, v43
	v_cvt_pk_bf16_f32 v152, v44, v45
	v_cvt_pk_bf16_f32 v153, v46, v47
	v_cvt_pk_bf16_f32 v154, v40, v41
	s_nop 0
	v_cvt_pk_bf16_f32 v155, v42, v43
	global_store_dwordx4 v[150:151], v[152:155], off nt
	v_pk_mul_f32 v[36:37], v[36:37], s[100:101]
	v_pk_mul_f32 v[38:39], v[38:39], s[100:101]
	v_pk_mul_f32 v[32:33], v[32:33], s[100:101]
	v_pk_mul_f32 v[34:35], v[34:35], s[100:101]
	v_exp_f32_e32 v36, v36
	v_exp_f32_e32 v37, v37
	v_exp_f32_e32 v38, v38
	v_exp_f32_e32 v39, v39
	v_exp_f32_e32 v32, v32
	v_exp_f32_e32 v33, v33
	v_exp_f32_e32 v34, v34
	v_exp_f32_e32 v35, v35
	v_pk_add_f32 v[36:37], v[36:37], 1.0 op_sel_hi:[1,0]
	v_pk_add_f32 v[38:39], v[38:39], 1.0 op_sel_hi:[1,0]
	v_pk_add_f32 v[32:33], v[32:33], 1.0 op_sel_hi:[1,0]
	v_pk_add_f32 v[34:35], v[34:35], 1.0 op_sel_hi:[1,0]
	v_rcp_f32_e32 v36, v36
	v_rcp_f32_e32 v37, v37
	v_rcp_f32_e32 v38, v38
	v_rcp_f32_e32 v39, v39
	v_rcp_f32_e32 v32, v32
	v_rcp_f32_e32 v33, v33
	v_rcp_f32_e32 v34, v34
	v_rcp_f32_e32 v35, v35
	v_cvt_pk_bf16_f32 v164, v36, v37
	v_cvt_pk_bf16_f32 v165, v38, v39
	v_cvt_pk_bf16_f32 v166, v32, v33
	s_nop 0
	v_cvt_pk_bf16_f32 v167, v34, v35
	global_store_dwordx4 v[150:151], v[164:167], off offset:256 nt
	s_mov_b32 s98, 0xa0000
	v_lshl_add_u64 v[150:151], v[148:149], 0, s[98:99]
	v_pk_mul_f32 v[28:29], v[28:29], s[100:101]
	v_pk_mul_f32 v[30:31], v[30:31], s[100:101]
	v_pk_mul_f32 v[24:25], v[24:25], s[100:101]
	v_pk_mul_f32 v[26:27], v[26:27], s[100:101]
	v_exp_f32_e32 v28, v28
	v_exp_f32_e32 v29, v29
	v_exp_f32_e32 v30, v30
	v_exp_f32_e32 v31, v31
	v_exp_f32_e32 v24, v24
	v_exp_f32_e32 v25, v25
	v_exp_f32_e32 v26, v26
	v_exp_f32_e32 v27, v27
	v_pk_add_f32 v[28:29], v[28:29], 1.0 op_sel_hi:[1,0]
	v_pk_add_f32 v[30:31], v[30:31], 1.0 op_sel_hi:[1,0]
	v_pk_add_f32 v[24:25], v[24:25], 1.0 op_sel_hi:[1,0]
	v_pk_add_f32 v[26:27], v[26:27], 1.0 op_sel_hi:[1,0]
	v_rcp_f32_e32 v28, v28
	v_rcp_f32_e32 v29, v29
	v_rcp_f32_e32 v30, v30
	v_rcp_f32_e32 v31, v31
	v_rcp_f32_e32 v24, v24
	v_rcp_f32_e32 v25, v25
	v_rcp_f32_e32 v26, v26
	v_rcp_f32_e32 v27, v27
	v_cvt_pk_bf16_f32 v152, v28, v29
	v_cvt_pk_bf16_f32 v153, v30, v31
	v_cvt_pk_bf16_f32 v154, v24, v25
	s_nop 0
	v_cvt_pk_bf16_f32 v155, v26, v27
	global_store_dwordx4 v[150:151], v[152:155], off nt
	v_pk_mul_f32 v[20:21], v[20:21], s[100:101]
	v_pk_mul_f32 v[22:23], v[22:23], s[100:101]
	v_pk_mul_f32 v[16:17], v[16:17], s[100:101]
	v_pk_mul_f32 v[18:19], v[18:19], s[100:101]
	v_exp_f32_e32 v20, v20
	v_exp_f32_e32 v21, v21
	v_exp_f32_e32 v22, v22
	v_exp_f32_e32 v23, v23
	v_exp_f32_e32 v16, v16
	v_exp_f32_e32 v17, v17
	v_exp_f32_e32 v18, v18
	v_exp_f32_e32 v19, v19
	v_pk_add_f32 v[20:21], v[20:21], 1.0 op_sel_hi:[1,0]
	v_pk_add_f32 v[22:23], v[22:23], 1.0 op_sel_hi:[1,0]
	v_pk_add_f32 v[16:17], v[16:17], 1.0 op_sel_hi:[1,0]
	v_pk_add_f32 v[18:19], v[18:19], 1.0 op_sel_hi:[1,0]
	v_rcp_f32_e32 v20, v20
	v_rcp_f32_e32 v21, v21
	v_rcp_f32_e32 v22, v22
	v_rcp_f32_e32 v23, v23
	v_rcp_f32_e32 v16, v16
	v_rcp_f32_e32 v17, v17
	v_rcp_f32_e32 v18, v18
	v_rcp_f32_e32 v19, v19
	v_cvt_pk_bf16_f32 v164, v20, v21
	v_cvt_pk_bf16_f32 v165, v22, v23
	v_cvt_pk_bf16_f32 v166, v16, v17
	s_nop 0
	v_cvt_pk_bf16_f32 v167, v18, v19
	global_store_dwordx4 v[150:151], v[164:167], off offset:256 nt
	s_mov_b32 s98, 0xb0000
	v_lshl_add_u64 v[150:151], v[148:149], 0, s[98:99]
	v_pk_mul_f32 v[12:13], v[12:13], s[100:101]
	v_pk_mul_f32 v[14:15], v[14:15], s[100:101]
	v_pk_mul_f32 v[8:9], v[8:9], s[100:101]
	v_pk_mul_f32 v[10:11], v[10:11], s[100:101]
	v_exp_f32_e32 v12, v12
	v_exp_f32_e32 v13, v13
	v_exp_f32_e32 v14, v14
	v_exp_f32_e32 v15, v15
	v_exp_f32_e32 v8, v8
	v_exp_f32_e32 v9, v9
	v_exp_f32_e32 v10, v10
	v_exp_f32_e32 v11, v11
	v_pk_add_f32 v[12:13], v[12:13], 1.0 op_sel_hi:[1,0]
	v_pk_add_f32 v[14:15], v[14:15], 1.0 op_sel_hi:[1,0]
	v_pk_add_f32 v[8:9], v[8:9], 1.0 op_sel_hi:[1,0]
	v_pk_add_f32 v[10:11], v[10:11], 1.0 op_sel_hi:[1,0]
	v_rcp_f32_e32 v12, v12
	v_rcp_f32_e32 v13, v13
	v_rcp_f32_e32 v14, v14
	v_rcp_f32_e32 v15, v15
	v_rcp_f32_e32 v8, v8
	v_rcp_f32_e32 v9, v9
	v_rcp_f32_e32 v10, v10
	v_rcp_f32_e32 v11, v11
	v_cvt_pk_bf16_f32 v152, v12, v13
	v_cvt_pk_bf16_f32 v153, v14, v15
	v_cvt_pk_bf16_f32 v154, v8, v9
	s_nop 0
	v_cvt_pk_bf16_f32 v155, v10, v11
	global_store_dwordx4 v[150:151], v[152:155], off nt
	v_pk_mul_f32 v[4:5], v[4:5], s[100:101]
	v_pk_mul_f32 v[6:7], v[6:7], s[100:101]
	v_pk_mul_f32 v[0:1], v[0:1], s[100:101]
	v_pk_mul_f32 v[2:3], v[2:3], s[100:101]
	v_exp_f32_e32 v4, v4
	v_exp_f32_e32 v5, v5
	v_exp_f32_e32 v6, v6
	v_exp_f32_e32 v7, v7
	v_exp_f32_e32 v0, v0
	v_exp_f32_e32 v1, v1
	v_exp_f32_e32 v2, v2
	v_exp_f32_e32 v3, v3
	v_pk_add_f32 v[4:5], v[4:5], 1.0 op_sel_hi:[1,0]
	v_pk_add_f32 v[6:7], v[6:7], 1.0 op_sel_hi:[1,0]
	v_pk_add_f32 v[0:1], v[0:1], 1.0 op_sel_hi:[1,0]
	v_pk_add_f32 v[2:3], v[2:3], 1.0 op_sel_hi:[1,0]
	v_rcp_f32_e32 v4, v4
	v_rcp_f32_e32 v5, v5
	v_rcp_f32_e32 v6, v6
	v_rcp_f32_e32 v7, v7
	v_rcp_f32_e32 v0, v0
	v_rcp_f32_e32 v1, v1
	v_rcp_f32_e32 v2, v2
	v_rcp_f32_e32 v3, v3
	v_cvt_pk_bf16_f32 v164, v4, v5
	v_cvt_pk_bf16_f32 v165, v6, v7
	v_cvt_pk_bf16_f32 v166, v0, v1
	s_nop 0
	v_cvt_pk_bf16_f32 v167, v2, v3
	global_store_dwordx4 v[150:151], v[164:167], off offset:256 nt
	s_branch .Luhy_join

.LBB0_1104:
	v_add_u32_e32 v136, s40, v152
	v_ashrrev_i32_e32 v148, 1, v136
	v_and_b32_e32 v148, 0xffffff80, v148
	v_ashrrev_i32_e32 v149, 31, v148
	v_and_b32_e32 v136, 0x7f, v136
	v_lshl_add_u64 v[148:149], v[148:149], 1, s[20:21]
	v_lshlrev_b32_e32 v136, 1, v136
	v_add_u32_e32 v156, s38, v150
	v_mul_u32_u24_e32 v156, 0x1600, v156
	v_add_u32_e32 v136, v136, v156
	s_mov_b32 s100, 0xbfb8aa3b
	s_mov_b32 s101, 0xbfb8aa3b
	s_mov_b32 s99, 0
	v_lshl_add_u64 v[148:149], v[148:149], 0, v[136:137]
	v_pk_mul_f32 v[156:157], v[124:125], s[100:101]
	v_pk_mul_f32 v[158:159], v[126:127], s[100:101]
	v_pk_mul_f32 v[160:161], v[120:121], s[100:101]
	v_pk_mul_f32 v[162:163], v[122:123], s[100:101]
	v_exp_f32_e32 v156, v156
	v_exp_f32_e32 v157, v157
	v_exp_f32_e32 v158, v158
	v_exp_f32_e32 v159, v159
	v_exp_f32_e32 v160, v160
	v_exp_f32_e32 v161, v161
	v_exp_f32_e32 v162, v162
	v_exp_f32_e32 v163, v163
	v_pk_add_f32 v[156:157], v[156:157], 1.0 op_sel_hi:[1,0]
	v_pk_add_f32 v[158:159], v[158:159], 1.0 op_sel_hi:[1,0]
	v_pk_add_f32 v[160:161], v[160:161], 1.0 op_sel_hi:[1,0]
	v_pk_add_f32 v[162:163], v[162:163], 1.0 op_sel_hi:[1,0]
	v_rcp_f32_e32 v156, v156
	v_rcp_f32_e32 v157, v157
	v_rcp_f32_e32 v158, v158
	v_rcp_f32_e32 v159, v159
	v_rcp_f32_e32 v160, v160
	v_rcp_f32_e32 v161, v161
	v_rcp_f32_e32 v162, v162
	v_rcp_f32_e32 v163, v163
	v_pk_mul_f32 v[156:157], v[124:125], v[156:157]
	v_pk_mul_f32 v[158:159], v[126:127], v[158:159]
	v_pk_mul_f32 v[160:161], v[120:121], v[160:161]
	v_pk_mul_f32 v[162:163], v[122:123], v[162:163]
	v_pk_mul_f32 v[156:157], v[156:157], v[116:117]
	v_pk_mul_f32 v[158:159], v[158:159], v[118:119]
	v_pk_mul_f32 v[160:161], v[160:161], v[112:113]
	v_pk_mul_f32 v[162:163], v[162:163], v[114:115]
	v_cvt_pk_bf16_f32 v156, v156, v157
	v_cvt_pk_bf16_f32 v157, v158, v159
	v_cvt_pk_bf16_f32 v158, v160, v161
	v_cvt_pk_bf16_f32 v159, v162, v163
	global_store_dwordx4 v[148:149], v[156:159], off nt
	s_mov_b32 s98, 0x16000
	v_lshl_add_u64 v[172:173], v[148:149], 0, s[98:99]
	v_pk_mul_f32 v[164:165], v[108:109], s[100:101]
	v_pk_mul_f32 v[166:167], v[110:111], s[100:101]
	v_pk_mul_f32 v[168:169], v[104:105], s[100:101]
	v_pk_mul_f32 v[170:171], v[106:107], s[100:101]
	v_exp_f32_e32 v164, v164
	v_exp_f32_e32 v165, v165
	v_exp_f32_e32 v166, v166
	v_exp_f32_e32 v167, v167
	v_exp_f32_e32 v168, v168
	v_exp_f32_e32 v169, v169
	v_exp_f32_e32 v170, v170
	v_exp_f32_e32 v171, v171
	v_pk_add_f32 v[164:165], v[164:165], 1.0 op_sel_hi:[1,0]
	v_pk_add_f32 v[166:167], v[166:167], 1.0 op_sel_hi:[1,0]
	v_pk_add_f32 v[168:169], v[168:169], 1.0 op_sel_hi:[1,0]
	v_pk_add_f32 v[170:171], v[170:171], 1.0 op_sel_hi:[1,0]
	v_rcp_f32_e32 v164, v164
	v_rcp_f32_e32 v165, v165
	v_rcp_f32_e32 v166, v166
	v_rcp_f32_e32 v167, v167
	v_rcp_f32_e32 v168, v168
	v_rcp_f32_e32 v169, v169
	v_rcp_f32_e32 v170, v170
	v_rcp_f32_e32 v171, v171
	v_pk_mul_f32 v[164:165], v[108:109], v[164:165]
	v_pk_mul_f32 v[166:167], v[110:111], v[166:167]
	v_pk_mul_f32 v[168:169], v[104:105], v[168:169]
	v_pk_mul_f32 v[170:171], v[106:107], v[170:171]
	v_pk_mul_f32 v[164:165], v[164:165], v[100:101]
	v_pk_mul_f32 v[166:167], v[166:167], v[102:103]
	v_pk_mul_f32 v[168:169], v[168:169], v[96:97]
	v_pk_mul_f32 v[170:171], v[170:171], v[98:99]
	v_cvt_pk_bf16_f32 v164, v164, v165
	v_cvt_pk_bf16_f32 v165, v166, v167
	v_cvt_pk_bf16_f32 v166, v168, v169
	v_cvt_pk_bf16_f32 v167, v170, v171
	global_store_dwordx4 v[172:173], v[164:167], off nt
	s_mov_b32 s98, 0x2c000
	v_lshl_add_u64 v[172:173], v[148:149], 0, s[98:99]
	v_pk_mul_f32 v[156:157], v[92:93], s[100:101]
	v_pk_mul_f32 v[158:159], v[94:95], s[100:101]
	v_pk_mul_f32 v[160:161], v[88:89], s[100:101]
	v_pk_mul_f32 v[162:163], v[90:91], s[100:101]
	v_exp_f32_e32 v156, v156
	v_exp_f32_e32 v157, v157
	v_exp_f32_e32 v158, v158
	v_exp_f32_e32 v159, v159
	v_exp_f32_e32 v160, v160
	v_exp_f32_e32 v161, v161
	v_exp_f32_e32 v162, v162
	v_exp_f32_e32 v163, v163
	v_pk_add_f32 v[156:157], v[156:157], 1.0 op_sel_hi:[1,0]
	v_pk_add_f32 v[158:159], v[158:159], 1.0 op_sel_hi:[1,0]
	v_pk_add_f32 v[160:161], v[160:161], 1.0 op_sel_hi:[1,0]
	v_pk_add_f32 v[162:163], v[162:163], 1.0 op_sel_hi:[1,0]
	v_rcp_f32_e32 v156, v156
	v_rcp_f32_e32 v157, v157
	v_rcp_f32_e32 v158, v158
	v_rcp_f32_e32 v159, v159
	v_rcp_f32_e32 v160, v160
	v_rcp_f32_e32 v161, v161
	v_rcp_f32_e32 v162, v162
	v_rcp_f32_e32 v163, v163
	v_pk_mul_f32 v[156:157], v[92:93], v[156:157]
	v_pk_mul_f32 v[158:159], v[94:95], v[158:159]
	v_pk_mul_f32 v[160:161], v[88:89], v[160:161]
	v_pk_mul_f32 v[162:163], v[90:91], v[162:163]
	v_pk_mul_f32 v[156:157], v[156:157], v[84:85]
	v_pk_mul_f32 v[158:159], v[158:159], v[86:87]
	v_pk_mul_f32 v[160:161], v[160:161], v[80:81]
	v_pk_mul_f32 v[162:163], v[162:163], v[82:83]
	v_cvt_pk_bf16_f32 v156, v156, v157
	v_cvt_pk_bf16_f32 v157, v158, v159
	v_cvt_pk_bf16_f32 v158, v160, v161
	v_cvt_pk_bf16_f32 v159, v162, v163
	global_store_dwordx4 v[172:173], v[156:159], off nt
	s_mov_b32 s98, 0x42000
	v_lshl_add_u64 v[172:173], v[148:149], 0, s[98:99]
	v_pk_mul_f32 v[164:165], v[76:77], s[100:101]
	v_pk_mul_f32 v[166:167], v[78:79], s[100:101]
	v_pk_mul_f32 v[168:169], v[72:73], s[100:101]
	v_pk_mul_f32 v[170:171], v[74:75], s[100:101]
	v_exp_f32_e32 v164, v164
	v_exp_f32_e32 v165, v165
	v_exp_f32_e32 v166, v166
	v_exp_f32_e32 v167, v167
	v_exp_f32_e32 v168, v168
	v_exp_f32_e32 v169, v169
	v_exp_f32_e32 v170, v170
	v_exp_f32_e32 v171, v171
	v_pk_add_f32 v[164:165], v[164:165], 1.0 op_sel_hi:[1,0]
	v_pk_add_f32 v[166:167], v[166:167], 1.0 op_sel_hi:[1,0]
	v_pk_add_f32 v[168:169], v[168:169], 1.0 op_sel_hi:[1,0]
	v_pk_add_f32 v[170:171], v[170:171], 1.0 op_sel_hi:[1,0]
	v_rcp_f32_e32 v164, v164
	v_rcp_f32_e32 v165, v165
	v_rcp_f32_e32 v166, v166
	v_rcp_f32_e32 v167, v167
	v_rcp_f32_e32 v168, v168
	v_rcp_f32_e32 v169, v169
	v_rcp_f32_e32 v170, v170
	v_rcp_f32_e32 v171, v171
	v_pk_mul_f32 v[164:165], v[76:77], v[164:165]
	v_pk_mul_f32 v[166:167], v[78:79], v[166:167]
	v_pk_mul_f32 v[168:169], v[72:73], v[168:169]
	v_pk_mul_f32 v[170:171], v[74:75], v[170:171]
	v_pk_mul_f32 v[164:165], v[164:165], v[68:69]
	v_pk_mul_f32 v[166:167], v[166:167], v[70:71]
	v_pk_mul_f32 v[168:169], v[168:169], v[64:65]
	v_pk_mul_f32 v[170:171], v[170:171], v[66:67]
	v_cvt_pk_bf16_f32 v164, v164, v165
	v_cvt_pk_bf16_f32 v165, v166, v167
	v_cvt_pk_bf16_f32 v166, v168, v169
	v_cvt_pk_bf16_f32 v167, v170, v171
	global_store_dwordx4 v[172:173], v[164:167], off nt
	s_mov_b32 s98, 0xb0000
	v_lshl_add_u64 v[172:173], v[148:149], 0, s[98:99]
	v_pk_mul_f32 v[156:157], v[60:61], s[100:101]
	v_pk_mul_f32 v[158:159], v[62:63], s[100:101]
	v_pk_mul_f32 v[160:161], v[56:57], s[100:101]
	v_pk_mul_f32 v[162:163], v[58:59], s[100:101]
	v_exp_f32_e32 v156, v156
	v_exp_f32_e32 v157, v157
	v_exp_f32_e32 v158, v158
	v_exp_f32_e32 v159, v159
	v_exp_f32_e32 v160, v160
	v_exp_f32_e32 v161, v161
	v_exp_f32_e32 v162, v162
	v_exp_f32_e32 v163, v163
	v_pk_add_f32 v[156:157], v[156:157], 1.0 op_sel_hi:[1,0]
	v_pk_add_f32 v[158:159], v[158:159], 1.0 op_sel_hi:[1,0]
	v_pk_add_f32 v[160:161], v[160:161], 1.0 op_sel_hi:[1,0]
	v_pk_add_f32 v[162:163], v[162:163], 1.0 op_sel_hi:[1,0]
	v_rcp_f32_e32 v156, v156
	v_rcp_f32_e32 v157, v157
	v_rcp_f32_e32 v158, v158
	v_rcp_f32_e32 v159, v159
	v_rcp_f32_e32 v160, v160
	v_rcp_f32_e32 v161, v161
	v_rcp_f32_e32 v162, v162
	v_rcp_f32_e32 v163, v163
	v_pk_mul_f32 v[156:157], v[60:61], v[156:157]
	v_pk_mul_f32 v[158:159], v[62:63], v[158:159]
	v_pk_mul_f32 v[160:161], v[56:57], v[160:161]
	v_pk_mul_f32 v[162:163], v[58:59], v[162:163]
	v_pk_mul_f32 v[156:157], v[156:157], v[52:53]
	v_pk_mul_f32 v[158:159], v[158:159], v[54:55]
	v_pk_mul_f32 v[160:161], v[160:161], v[48:49]
	v_pk_mul_f32 v[162:163], v[162:163], v[50:51]
	v_cvt_pk_bf16_f32 v156, v156, v157
	v_cvt_pk_bf16_f32 v157, v158, v159
	v_cvt_pk_bf16_f32 v158, v160, v161
	v_cvt_pk_bf16_f32 v159, v162, v163
	global_store_dwordx4 v[172:173], v[156:159], off nt
	s_mov_b32 s98, 0xc6000
	v_lshl_add_u64 v[172:173], v[148:149], 0, s[98:99]
	v_pk_mul_f32 v[164:165], v[44:45], s[100:101]
	v_pk_mul_f32 v[166:167], v[46:47], s[100:101]
	v_pk_mul_f32 v[168:169], v[40:41], s[100:101]
	v_pk_mul_f32 v[170:171], v[42:43], s[100:101]
	v_exp_f32_e32 v164, v164
	v_exp_f32_e32 v165, v165
	v_exp_f32_e32 v166, v166
	v_exp_f32_e32 v167, v167
	v_exp_f32_e32 v168, v168
	v_exp_f32_e32 v169, v169
	v_exp_f32_e32 v170, v170
	v_exp_f32_e32 v171, v171
	v_pk_add_f32 v[164:165], v[164:165], 1.0 op_sel_hi:[1,0]
	v_pk_add_f32 v[166:167], v[166:167], 1.0 op_sel_hi:[1,0]
	v_pk_add_f32 v[168:169], v[168:169], 1.0 op_sel_hi:[1,0]
	v_pk_add_f32 v[170:171], v[170:171], 1.0 op_sel_hi:[1,0]
	v_rcp_f32_e32 v164, v164
	v_rcp_f32_e32 v165, v165
	v_rcp_f32_e32 v166, v166
	v_rcp_f32_e32 v167, v167
	v_rcp_f32_e32 v168, v168
	v_rcp_f32_e32 v169, v169
	v_rcp_f32_e32 v170, v170
	v_rcp_f32_e32 v171, v171
	v_pk_mul_f32 v[164:165], v[44:45], v[164:165]
	v_pk_mul_f32 v[166:167], v[46:47], v[166:167]
	v_pk_mul_f32 v[168:169], v[40:41], v[168:169]
	v_pk_mul_f32 v[170:171], v[42:43], v[170:171]
	v_pk_mul_f32 v[164:165], v[164:165], v[36:37]
	v_pk_mul_f32 v[166:167], v[166:167], v[38:39]
	v_pk_mul_f32 v[168:169], v[168:169], v[32:33]
	v_pk_mul_f32 v[170:171], v[170:171], v[34:35]
	v_cvt_pk_bf16_f32 v164, v164, v165
	v_cvt_pk_bf16_f32 v165, v166, v167
	v_cvt_pk_bf16_f32 v166, v168, v169
	v_cvt_pk_bf16_f32 v167, v170, v171
	global_store_dwordx4 v[172:173], v[164:167], off nt
	s_mov_b32 s98, 0xdc000
	v_lshl_add_u64 v[172:173], v[148:149], 0, s[98:99]
	v_pk_mul_f32 v[156:157], v[28:29], s[100:101]
	v_pk_mul_f32 v[158:159], v[30:31], s[100:101]
	v_pk_mul_f32 v[160:161], v[24:25], s[100:101]
	v_pk_mul_f32 v[162:163], v[26:27], s[100:101]
	v_exp_f32_e32 v156, v156
	v_exp_f32_e32 v157, v157
	v_exp_f32_e32 v158, v158
	v_exp_f32_e32 v159, v159
	v_exp_f32_e32 v160, v160
	v_exp_f32_e32 v161, v161
	v_exp_f32_e32 v162, v162
	v_exp_f32_e32 v163, v163
	v_pk_add_f32 v[156:157], v[156:157], 1.0 op_sel_hi:[1,0]
	v_pk_add_f32 v[158:159], v[158:159], 1.0 op_sel_hi:[1,0]
	v_pk_add_f32 v[160:161], v[160:161], 1.0 op_sel_hi:[1,0]
	v_pk_add_f32 v[162:163], v[162:163], 1.0 op_sel_hi:[1,0]
	v_rcp_f32_e32 v156, v156
	v_rcp_f32_e32 v157, v157
	v_rcp_f32_e32 v158, v158
	v_rcp_f32_e32 v159, v159
	v_rcp_f32_e32 v160, v160
	v_rcp_f32_e32 v161, v161
	v_rcp_f32_e32 v162, v162
	v_rcp_f32_e32 v163, v163
	v_pk_mul_f32 v[156:157], v[28:29], v[156:157]
	v_pk_mul_f32 v[158:159], v[30:31], v[158:159]
	v_pk_mul_f32 v[160:161], v[24:25], v[160:161]
	v_pk_mul_f32 v[162:163], v[26:27], v[162:163]
	v_pk_mul_f32 v[156:157], v[156:157], v[20:21]
	v_pk_mul_f32 v[158:159], v[158:159], v[22:23]
	v_pk_mul_f32 v[160:161], v[160:161], v[16:17]
	v_pk_mul_f32 v[162:163], v[162:163], v[18:19]
	v_cvt_pk_bf16_f32 v156, v156, v157
	v_cvt_pk_bf16_f32 v157, v158, v159
	v_cvt_pk_bf16_f32 v158, v160, v161
	v_cvt_pk_bf16_f32 v159, v162, v163
	global_store_dwordx4 v[172:173], v[156:159], off nt
	s_mov_b32 s98, 0xf2000
	v_lshl_add_u64 v[172:173], v[148:149], 0, s[98:99]
	v_pk_mul_f32 v[164:165], v[12:13], s[100:101]
	v_pk_mul_f32 v[166:167], v[14:15], s[100:101]
	v_pk_mul_f32 v[168:169], v[8:9], s[100:101]
	v_pk_mul_f32 v[170:171], v[10:11], s[100:101]
	v_exp_f32_e32 v164, v164
	v_exp_f32_e32 v165, v165
	v_exp_f32_e32 v166, v166
	v_exp_f32_e32 v167, v167
	v_exp_f32_e32 v168, v168
	v_exp_f32_e32 v169, v169
	v_exp_f32_e32 v170, v170
	v_exp_f32_e32 v171, v171
	v_pk_add_f32 v[164:165], v[164:165], 1.0 op_sel_hi:[1,0]
	v_pk_add_f32 v[166:167], v[166:167], 1.0 op_sel_hi:[1,0]
	v_pk_add_f32 v[168:169], v[168:169], 1.0 op_sel_hi:[1,0]
	v_pk_add_f32 v[170:171], v[170:171], 1.0 op_sel_hi:[1,0]
	v_rcp_f32_e32 v164, v164
	v_rcp_f32_e32 v165, v165
	v_rcp_f32_e32 v166, v166
	v_rcp_f32_e32 v167, v167
	v_rcp_f32_e32 v168, v168
	v_rcp_f32_e32 v169, v169
	v_rcp_f32_e32 v170, v170
	v_rcp_f32_e32 v171, v171
	v_pk_mul_f32 v[164:165], v[12:13], v[164:165]
	v_pk_mul_f32 v[166:167], v[14:15], v[166:167]
	v_pk_mul_f32 v[168:169], v[8:9], v[168:169]
	v_pk_mul_f32 v[170:171], v[10:11], v[170:171]
	v_pk_mul_f32 v[164:165], v[164:165], v[4:5]
	v_pk_mul_f32 v[166:167], v[166:167], v[6:7]
	v_pk_mul_f32 v[168:169], v[168:169], v[0:1]
	v_pk_mul_f32 v[170:171], v[170:171], v[2:3]
	v_cvt_pk_bf16_f32 v164, v164, v165
	v_cvt_pk_bf16_f32 v165, v166, v167
	v_cvt_pk_bf16_f32 v166, v168, v169
	v_cvt_pk_bf16_f32 v167, v170, v171
	global_store_dwordx4 v[172:173], v[164:167], off nt
	s_andn2_b64 vcc, exec, s[0:1]
	s_mov_b64 s[0:1], -1
	s_mov_b32 s101, 1
	s_cbranch_vccnz .LBB0_1097
	s_andn2_b64 vcc, exec, s[8:9]
	s_cbranch_vccnz .LBB0_1096
	s_barrier
	s_branch .LBB0_1096
